# MM1 on PL1+PW1 (R0=28672): channel-map routine on waves 0-3 of all 256 workgroups, its closing barrier dropped, so every workgroup's waves 4-7 stream from the start
# speedup vs baseline: 1.0048x; 1.0048x over previous
; #define LAS __attribute__((address_space(3)))
; __device__ void p0_mmat(const Args& a, LAS unsigned char* lds) {
;     LAS float* ct = (LAS float*)lds; LAS float* st = ct + 128;
;     int tid_ = threadIdx.x; asm volatile("" : "+v"(tid_)); const int tid = tid_;
;     if (tid < 128) { float s, c; sincospif((float)tid * (1.0f / 64.0f), &s, &c); ct[tid] = c; st[tid] = s; }
;     __syncthreads();
;     float* MM = (float*)(a.ws + WS_MM);
;     const int total = 2 * 4 * 128 * 64;
;     for (int idx = blockIdx.x * NTHREADS + tid; idx < total; idx += gridDim.x * NTHREADS) {
;         const int d4 = idx & 63, cp = (idx >> 6) & 127, lg = idx >> 13;
;         const float* W = a.w_four + (size_t)lg * 128 * 128 + 4 * (d4 & 31);
;         const LAS float* tb = (d4 < 32) ? ct : st;
;         f32x4 acc = {0.f, 0.f, 0.f, 0.f};
; #pragma unroll 8
;         for (int c = 0; c < 128; ++c) acc += *(const f32x4*)(W + c * 128) * tb[(cp * c) & 127];
;         *(f32x4*)(MM + ((size_t)(lg * 128 + cp) * 256 + 4 * d4)) = acc * 0.08838834764831845f;
.LBB0_8:
	s_or_b64 exec, exec, s[4:5]
	s_lshl_b32 s3, s2, 8
	v_add_u32_e32 v1, s3, v6
	s_mov_b32 s4, 0x10000
	v_cmp_gt_i32_e32 vcc, s4, v1
	s_movk_i32 s9, 0x100
	v_cmp_gt_u32_e64 s[6:7], s9, v6
	s_and_b64 vcc, vcc, s[6:7]
	s_waitcnt lgkmcnt(0)
	s_barrier
	s_and_saveexec_b64 s[4:5], vcc
	s_cbranch_execz .LBB0_13
	s_load_dword s10, s[0:1], 0x60
	v_and_b32_e32 v2, 63, v6
	s_add_i32 s6, 0, 0x200
	v_mov_b32_e32 v3, s6
	v_cmp_gt_u32_e32 vcc, 32, v2
	v_lshlrev_b32_e32 v2, 4, v2
	s_mov_b64 s[6:7], 0x20a00000
	v_cndmask_b32_e64 v14, v3, 0, vcc
	v_mov_b32_e32 v3, 0
	v_lshl_add_u64 v[4:5], s[40:41], 0, v[2:3]
	v_lshlrev_b32_e32 v2, 2, v6
	s_waitcnt lgkmcnt(0)
	s_lshl_b32 s9, s10, 9
	v_lshl_add_u64 v[4:5], v[4:5], 0, s[6:7]
	v_lshl_add_u32 v2, s2, 10, v2
	s_lshl_b32 s11, s10, 11
	s_mov_b64 s[6:7], 0
	s_movk_i32 s33, 0x1f0
	s_mov_b32 s10, 0x3db504f3
	s_mov_b32 s34, 0xffff

; __device__ void p0_mmat(const Args& a, LAS unsigned char* lds) {
;     ...
;     __syncthreads();
; __global__ void __launch_bounds__(NTHREADS, 2) hymba_fwd(Args a) {
;     ...
;     if (IN(0)) { p0_mmat(a, lds); p0_rope(a); p0_twiddle(a); p_weights_plain(a); }
.LBB0_13:
	s_or_b64 exec, exec, s[4:5]
	v_readfirstlane_b32 s100, v0
	s_nop 3
	s_cmp_ge_u32 s100, 0x100
	s_cbranch_scc1 .Lws_x
	s_mov_b32 s101, 0
